# HGRN pass-1 and pass-3 state loops: the 32 packed f32 multiplies that sit between MFMAs split into plain v_mul_f32 pairs (same f32 math)
# speedup vs baseline: 1.0074x; 1.0074x over previous
; template <int PASS>
; DEV void hgrn_task(unsigned char* lds, int task, int l, const bf16_t* BZ, float* E, float* Dd, float* OF, bf16_t* YB, const float* b_lb, const float* gout) {
;     ...
; #pragma unroll
;                     for (int mt = 0; mt < 8; ++mt) { const f32x4 d = *(const f32x4*)(DECj + 16 * mt + 4 * fq); const s16x4 kef = *(const s16x4*)(KETj + (16 * mt + fr) * 16 + 4 * fq);
;                         const bf16x8 ke8 = {kef[0], kef[1], kef[2], kef[3], 0, 0, 0, 0}; const bf16x8 vu8 = {vf[0], vf[1], vf[2], vf[3], 0, 0, 0, 0};
;                         st[mt] = __builtin_amdgcn_mfma_f32_16x16x32_bf16(ke8, vu8, st[mt] * d, 0, 0, 0); }
.LBB0_502:
	v_add_u32_e32 v51, s5, v109
	ds_read_b64 v[126:127], v49
	ds_read_b128 v[134:137], v51
	ds_read2st64_b64 v[138:141], v45 offset1:1
	v_mov_b32_e32 v129, v128
	v_mov_b32_e32 v144, v128
	v_mov_b32_e32 v145, v128
	s_waitcnt lgkmcnt(1)
	v_mul_f32_e32 v30, v30, v136
	v_mul_f32_e32 v31, v31, v137
	v_mul_f32_e32 v28, v28, v134
	v_mul_f32_e32 v29, v29, v135
	ds_read_b128 v[134:137], v51 offset:64
	s_waitcnt lgkmcnt(1)
	v_mov_b32_e32 v142, v138
	v_mov_b32_e32 v143, v139
	v_mov_b32_e32 v138, v140
	v_mov_b32_e32 v139, v141
	v_mov_b32_e32 v140, v128
	v_mov_b32_e32 v141, v128
	s_waitcnt lgkmcnt(0)
	v_mul_f32_e32 v26, v26, v136
	v_mul_f32_e32 v27, v27, v137
	v_mul_f32_e32 v24, v24, v134
	v_mul_f32_e32 v25, v25, v135
	v_mfma_f32_16x16x32_bf16 v[28:31], v[142:145], v[126:129], v[28:31]
	s_addk_i32 s5, 0x200
	v_add_u32_e32 v49, 0x800, v49
	s_cmpk_lg_i32 s5, 0x800
	v_mfma_f32_16x16x32_bf16 v[24:27], v[138:141], v[126:129], v[24:27]
	ds_read_b128 v[134:137], v51 offset:128
	ds_read2st64_b64 v[138:141], v45 offset0:2 offset1:3
	s_waitcnt lgkmcnt(1)
	v_mul_f32_e32 v22, v22, v136
	v_mul_f32_e32 v23, v23, v137
	v_mul_f32_e32 v20, v20, v134
	v_mul_f32_e32 v21, v21, v135
	ds_read_b128 v[134:137], v51 offset:192
	s_waitcnt lgkmcnt(1)
	v_mov_b32_e32 v142, v138
	v_mov_b32_e32 v143, v139
	v_mov_b32_e32 v138, v140
	v_mov_b32_e32 v139, v141
	v_mov_b32_e32 v140, v128
	v_mov_b32_e32 v141, v128
	s_waitcnt lgkmcnt(0)
	v_mul_f32_e32 v18, v18, v136
	v_mul_f32_e32 v19, v19, v137
	v_mul_f32_e32 v16, v16, v134
	v_mul_f32_e32 v17, v17, v135
	v_mfma_f32_16x16x32_bf16 v[20:23], v[142:145], v[126:129], v[20:23]
	s_nop 0
	v_mfma_f32_16x16x32_bf16 v[16:19], v[138:141], v[126:129], v[16:19]
	ds_read_b128 v[134:137], v51 offset:256
	ds_read2st64_b64 v[138:141], v45 offset0:4 offset1:5
	s_waitcnt lgkmcnt(1)
	v_mul_f32_e32 v14, v14, v136
	v_mul_f32_e32 v15, v15, v137
	v_mul_f32_e32 v12, v12, v134
	v_mul_f32_e32 v13, v13, v135
	ds_read_b128 v[134:137], v51 offset:320
	s_waitcnt lgkmcnt(1)
	v_mov_b32_e32 v142, v138
	v_mov_b32_e32 v143, v139
	v_mov_b32_e32 v138, v140
	v_mov_b32_e32 v139, v141
	v_mov_b32_e32 v140, v128
	v_mov_b32_e32 v141, v128
	s_waitcnt lgkmcnt(0)
	v_mul_f32_e32 v10, v10, v136
	v_mul_f32_e32 v11, v11, v137
	v_mul_f32_e32 v8, v8, v134
	v_mul_f32_e32 v9, v9, v135
	v_mfma_f32_16x16x32_bf16 v[12:15], v[142:145], v[126:129], v[12:15]
	s_nop 0
	v_mfma_f32_16x16x32_bf16 v[8:11], v[138:141], v[126:129], v[8:11]
	ds_read_b128 v[134:137], v51 offset:384
	ds_read2st64_b64 v[138:141], v45 offset0:6 offset1:7
	v_add_u32_e32 v45, 0x1000, v45
	s_waitcnt lgkmcnt(1)
	v_mul_f32_e32 v6, v6, v136
	v_mul_f32_e32 v7, v7, v137
	v_mul_f32_e32 v4, v4, v134
	v_mul_f32_e32 v5, v5, v135
	ds_read_b128 v[134:137], v51 offset:448
	s_waitcnt lgkmcnt(1)
	v_mov_b32_e32 v142, v138
	v_mov_b32_e32 v143, v139
	v_mov_b32_e32 v138, v140
	v_mov_b32_e32 v139, v141
	v_mov_b32_e32 v140, v128
	v_mov_b32_e32 v141, v128
	s_waitcnt lgkmcnt(0)
	v_mul_f32_e32 v2, v2, v136
	v_mul_f32_e32 v3, v3, v137
	v_mul_f32_e32 v0, v0, v134
	v_mul_f32_e32 v1, v1, v135
	v_mfma_f32_16x16x32_bf16 v[4:7], v[142:145], v[126:129], v[4:7]
	s_nop 0
	v_mfma_f32_16x16x32_bf16 v[0:3], v[138:141], v[126:129], v[0:3]
	s_cbranch_scc1 .LBB0_502
	s_branch .LBB0_497

; template <int PASS>
; DEV void hgrn_task(unsigned char* lds, int task, int l, const bf16_t* BZ, float* E, float* Dd, float* OF, bf16_t* YB, const float* b_lb, const float* gout) {
;     ...
;                     const bf16_t* QDj = QD + j * 16 * QP; const bf16_t* KIj = KI + j * 16 * QP; const bf16_t* KETj = KET + j * 128 * 16; const bf16_t* VTj = VT + j * 64 * 16; const float* DECj = DEC + j * 128;
;                     const s16x4 vf = *(const s16x4*)(VTj + (16 * nt + fr) * 16 + 4 * fq);
;                     if (PASS == 3) {
;                         bf16x8 qd[4]; f32x4 sc = {0.f, 0.f, 0.f, 0.f};
; #pragma unroll
;                         for (int kk = 0; kk < 4; ++kk) { const s16x4 a0 = *(const s16x4*)(QDj + fr * QP + 32 * kk + 4 * fq), a1 = *(const s16x4*)(QDj + fr * QP + 32 * kk + 16 + 4 * fq);
;                             qd[kk] = (bf16x8){a0[0], a0[1], a0[2], a0[3], a1[0], a1[1], a1[2], a1[3]};
;                             const s16x4 b0 = *(const s16x4*)(KIj + fr * QP + 32 * kk + 4 * fq), b1 = *(const s16x4*)(KIj + fr * QP + 32 * kk + 16 + 4 * fq);
;                             const bf16x8 kf = {b0[0], b0[1], b0[2], b0[3], b1[0], b1[1], b1[2], b1[3]};
;                             sc = __builtin_amdgcn_mfma_f32_16x16x32_bf16(kf, qd[kk], sc, 0, 0, 0); asm volatile("" :: "v"(kf), "v"(qd[kk])); }
; #pragma unroll
;                         for (int i = 0; i < 4; ++i) if (4 * fq + i > fr) sc[i] = 0.f;
;                         u32x2 sw; sw.x = pk2b(sc[0], sc[1]); sw.y = pk2b(sc[2], sc[3]);
;                         const s16x4 swv = __builtin_bit_cast(s16x4, sw);
;                         f32x4 z4 = {0.f, 0.f, 0.f, 0.f}; asm volatile("" : "+v"(z4));
;                         const bf16x8 sw8 = {swv[0], swv[1], swv[2], swv[3], 0, 0, 0, 0}; const bf16x8 vf8 = {vf[0], vf[1], vf[2], vf[3], 0, 0, 0, 0};
;                         f32x4 oacc = __builtin_amdgcn_mfma_f32_16x16x32_bf16(sw8, vf8, z4, 0, 0, 0); asm volatile("" :: "v"(swv), "v"(vf));
; #pragma unroll
;                         for (int kk = 0; kk < 4; ++kk) { u32x4 sb; sb.x = pk2b(st[2 * kk][0], st[2 * kk][1]); sb.y = pk2b(st[2 * kk][2], st[2 * kk][3]); sb.z = pk2b(st[2 * kk + 1][0], st[2 * kk + 1][1]); sb.w = pk2b(st[2 * kk + 1][2], st[2 * kk + 1][3]);
.LBB0_574:
	v_add_u32_e32 v40, 0, v42
	v_add_u32_e32 v41, 0x4000, v40
	v_add_u32_e32 v38, 0, v43
	ds_read_b64 v[38:39], v38
	ds_read2_b64 v[48:51], v40 offset1:4
	ds_read2_b64 v[134:137], v41 offset0:128 offset1:132
	ds_read2_b64 v[114:117], v40 offset0:8 offset1:12
	ds_read2_b64 v[138:141], v41 offset0:136 offset1:140
	ds_read2_b64 v[122:125], v40 offset0:16 offset1:20
	ds_read2_b64 v[130:133], v40 offset0:24 offset1:28
	v_mov_b32_e32 v129, v128
	v_mov_b32_e32 v126, v128
	v_mov_b32_e32 v127, v128
	s_add_i32 s5, s5, -1
	v_add_u32_e32 v43, 0x800, v43
	v_add_u32_e32 v42, 0x1100, v42
	s_waitcnt lgkmcnt(4)
	v_mfma_f32_16x16x32_bf16 v[118:121], v[134:137], v[48:51], 0
	ds_read2_b64 v[134:137], v41 offset0:144 offset1:148
	s_waitcnt lgkmcnt(3)
	v_mfma_f32_16x16x32_bf16 v[118:121], v[138:141], v[114:117], v[118:121]
	ds_read2_b64 v[138:141], v41 offset0:152 offset1:156
	s_cmp_lg_u32 s5, 0
	s_waitcnt lgkmcnt(1)
	v_mfma_f32_16x16x32_bf16 v[118:121], v[134:137], v[122:125], v[118:121]
	v_mov_b32_e32 v40, s67
	s_waitcnt lgkmcnt(0)
	v_mfma_f32_16x16x32_bf16 v[118:121], v[138:141], v[130:133], v[118:121]
	v_mov_b64_e32 v[136:137], v[128:129]
	v_mov_b64_e32 v[134:135], v[126:127]
	s_nop 5
	v_cndmask_b32_e64 v40, v118, v40, s[8:9]
	v_cndmask_b32_e64 v40, v40, v118, s[10:11]
	v_cndmask_b32_e64 v41, 0, v119, s[10:11]
	v_cndmask_b32_e64 v47, v120, 0, s[12:13]
	v_cndmask_b32_e64 v52, v121, 0, s[14:15]
	v_cvt_pk_bf16_f32 v118, v40, v41
	v_cvt_pk_bf16_f32 v119, v47, v52
	v_mov_b32_e32 v120, v128
	v_mov_b32_e32 v121, v128
	v_mov_b32_e32 v40, v128
	v_mov_b32_e32 v41, v128
	ds_read_b128 v[138:141], v46
	s_nop 0
	v_mfma_f32_16x16x32_bf16 v[134:137], v[118:121], v[38:41], v[134:137]
	v_cvt_pk_bf16_f32 v118, v2, v3
	v_cvt_pk_bf16_f32 v119, v4, v5
	v_cvt_pk_bf16_f32 v120, v6, v7
	v_cvt_pk_bf16_f32 v121, v8, v9
	s_nop 1
	v_mfma_f32_16x16x32_bf16 v[134:137], v[48:51], v[118:121], v[134:137]
	v_cvt_pk_bf16_f32 v48, v10, v11
	v_cvt_pk_bf16_f32 v49, v12, v13
	v_cvt_pk_bf16_f32 v50, v14, v15
	v_cvt_pk_bf16_f32 v51, v16, v17
	s_nop 1
	v_mfma_f32_16x16x32_bf16 v[118:121], v[114:117], v[48:51], v[134:137]
	v_cvt_pk_bf16_f32 v48, v18, v19
	v_cvt_pk_bf16_f32 v49, v20, v21
	v_cvt_pk_bf16_f32 v50, v22, v23
	v_cvt_pk_bf16_f32 v51, v24, v25
	s_nop 1
	v_mfma_f32_16x16x32_bf16 v[114:117], v[122:125], v[48:51], v[118:121]
	ds_read2st64_b64 v[134:137], v45 offset1:1
	v_cvt_pk_bf16_f32 v48, v26, v27
	v_cvt_pk_bf16_f32 v49, v28, v29
	v_cvt_pk_bf16_f32 v50, v30, v31
	v_cvt_pk_bf16_f32 v51, v32, v33
	s_nop 1
	v_mfma_f32_16x16x32_bf16 v[114:117], v[130:133], v[48:51], v[114:117]
	ds_read2st64_b64 v[118:121], v45 offset0:2 offset1:3
	ds_read2st64_b64 v[122:125], v45 offset0:4 offset1:5
	ds_read2st64_b64 v[130:133], v45 offset0:6 offset1:7
	ds_read_b128 v[48:51], v46 offset:64
	s_nop 3
	ds_write_b32 v44, v114 offset:61440
	ds_write_b32 v44, v115 offset:61696
	ds_write_b32 v44, v116 offset:61952
	ds_write_b32 v44, v117 offset:62208
	ds_read_b128 v[114:117], v46 offset:128
	s_waitcnt lgkmcnt(9)
	v_mov_b32_e32 v126, v134
	v_mov_b32_e32 v127, v135
	v_mul_f32_e32 v4, v4, v140
	v_mul_f32_e32 v5, v5, v141
	v_mul_f32_e32 v2, v2, v138
	v_mul_f32_e32 v3, v3, v139
	ds_read_b128 v[138:141], v46 offset:192
	s_nop 0
	v_mfma_f32_16x16x32_bf16 v[2:5], v[126:129], v[38:41], v[2:5]
	s_waitcnt lgkmcnt(6)
	v_mov_b32_e32 v126, v136
	v_mov_b32_e32 v127, v137
	v_mul_f32_e32 v8, v8, v50
	v_mul_f32_e32 v9, v9, v51
	v_mul_f32_e32 v6, v6, v48
	v_mul_f32_e32 v7, v7, v49
	ds_read_b128 v[48:51], v46 offset:256
	s_nop 0
	v_mfma_f32_16x16x32_bf16 v[6:9], v[126:129], v[38:41], v[6:9]
	s_waitcnt lgkmcnt(2)
	v_mov_b32_e32 v126, v118
	v_mov_b32_e32 v127, v119
	v_mul_f32_e32 v12, v12, v116
	v_mul_f32_e32 v13, v13, v117
	v_mul_f32_e32 v10, v10, v114
	v_mul_f32_e32 v11, v11, v115
	ds_read_b128 v[114:117], v46 offset:320
	s_nop 0
	v_mfma_f32_16x16x32_bf16 v[10:13], v[126:129], v[38:41], v[10:13]
	s_waitcnt lgkmcnt(2)
	v_mov_b32_e32 v126, v120
	v_mov_b32_e32 v127, v121
	v_mul_f32_e32 v16, v16, v140
	v_mul_f32_e32 v17, v17, v141
	v_mul_f32_e32 v14, v14, v138
	v_mul_f32_e32 v15, v15, v139
	ds_read_b128 v[138:141], v46 offset:384
	s_nop 0
	v_mfma_f32_16x16x32_bf16 v[14:17], v[126:129], v[38:41], v[14:17]
	s_waitcnt lgkmcnt(2)
	v_mov_b32_e32 v126, v122
	v_mov_b32_e32 v127, v123
	v_mul_f32_e32 v20, v20, v50
	v_mul_f32_e32 v21, v21, v51
	v_mul_f32_e32 v18, v18, v48
	v_mul_f32_e32 v19, v19, v49
	ds_read_b128 v[48:51], v46 offset:448
	s_nop 0
	v_mfma_f32_16x16x32_bf16 v[18:21], v[126:129], v[38:41], v[18:21]
	s_waitcnt lgkmcnt(2)
	v_mov_b32_e32 v126, v124
	v_mov_b32_e32 v127, v125
	v_mul_f32_e32 v24, v24, v116
	v_mul_f32_e32 v25, v25, v117
	v_mul_f32_e32 v22, v22, v114
	v_mul_f32_e32 v23, v23, v115
	s_nop 1
	v_mfma_f32_16x16x32_bf16 v[22:25], v[126:129], v[38:41], v[22:25]
	s_waitcnt lgkmcnt(1)
	v_mov_b32_e32 v126, v130
	v_mov_b32_e32 v127, v131
	v_mul_f32_e32 v28, v28, v140
	v_mul_f32_e32 v29, v29, v141
	v_mul_f32_e32 v26, v26, v138
	v_mul_f32_e32 v27, v27, v139
	s_nop 1
	v_mfma_f32_16x16x32_bf16 v[26:29], v[126:129], v[38:41], v[26:29]
	s_waitcnt lgkmcnt(0)
	v_mov_b32_e32 v126, v132
	v_mov_b32_e32 v127, v133
	v_mul_f32_e32 v32, v32, v50
	v_mul_f32_e32 v33, v33, v51
	v_mul_f32_e32 v30, v30, v48
	v_mul_f32_e32 v31, v31, v49
	s_nop 1
	v_mfma_f32_16x16x32_bf16 v[30:33], v[126:129], v[38:41], v[30:33]
	v_add_u32_e32 v44, 0x1000, v44
	v_add_u32_e32 v45, 0x1000, v45
	v_add_u32_e32 v46, 0x200, v46
	s_cbranch_scc1 .LBB0_574
